# item-start loads (first K/V tile, Q rows, rope rows) issued before the workgroup barrier of the prologue, on top of the prologue reorder and first-tile rescale skip; hot loop unchanged at the same add
# baseline (speedup 1.0000x reference)
; __device__ __forceinline__ void attn_body(const bf16_t* __restrict__ Qb, const bf16_t* __restrict__ KVh, const bf16_t* __restrict__ KR, const float* __restrict__ ropeq,
;                                           bf16_t* __restrict__ Ob, int seq, char* lds, const int tid) {
;     ...
;     { const bf16_t* Qw = Qb + (size_t)(wid * QBLK + r32) * NQ + hi * 8;
; #pragma unroll
;       for (int d0 = 0; d0 < 4; ++d0) qr[d0] = *reinterpret_cast<const bf16x8*>(Qw + d0 * 16);
;       const u32x4 w1 = *reinterpret_cast<const u32x4*>(Qw + 64), w2 = *reinterpret_cast<const u32x4*>(Qw + 80);
;       float x1[8], x2[8]; unpack8(w1, x1); unpack8(w2, x2);
;       const float* rp = ropeq + (size_t)(wid * QBLK + r32) * 32 + hi * 8;
;       float y1[8], y2[8];
; #pragma unroll
;       for (int e = 0; e < 8; ++e) { const float c = rp[e], s = rp[16 + e]; y1[e] = x1[e] * c - x2[e] * s; y2[e] = x1[e] * s + x2[e] * c; }
;       u32x4 o1 = {pk2(y1[0], y1[1]), pk2(y1[2], y1[3]), pk2(y1[4], y1[5]), pk2(y1[6], y1[7])};
;       u32x4 o2 = {pk2(y2[0], y2[1]), pk2(y2[2], y2[3]), pk2(y2[4], y2[5]), pk2(y2[6], y2[7])};
;       qr[4] = *reinterpret_cast<bf16x8*>(&o1); qr[5] = *reinterpret_cast<bf16x8*>(&o2); }
;     const int sr = tid >> 4, c16 = tid & 15;
;     const bool isK = c16 < 8;
;     const int kst0 = KSWZ(sr, c16 * 16), kst1 = KSWZ(32 + sr, c16 * 16), vst0 = v_st(sr, (c16 & 7) * 8), vst1 = v_st(32 + sr, (c16 & 7) * 8);
;     const int rkey = (tid & 255) >> 2, rch = tid & 3; const int rst = KSWZ(rkey, 128 + rch * 16); const bool rwr = tid < 256;
;     const int vb0 = (int)(uintptr_t)V_lds + v_rd_base(lane);
;     struct { bf16x8 a0, a1, rr; } sr_[2];
;     ...
;     f32x16 pA0, pA1, pB0, pB1; float mnA, mnB, alA, alB; bf16x8 pa0, pa1, pa2, pa3; const int NT = seq / KVBLK;
;     constexpr int SE = 0, SO = 1;
;     SLOAD(SE, 0); asm volatile("s_waitcnt vmcnt(0)" ::: "memory"); SWRITE(0, SE); __syncthreads();
; __device__ __forceinline__ void phase_attn(const Ctx& C, PP p, char* lds_generic) {
;     ...
;     for (int it = C.vcu; it < 2048; it += C.G) {
;         const int qb = it & 15, h = (it >> 4) & 15, b = it >> 8; const size_t t0 = (size_t)b * SEQ, q0 = t0 + qb * 256;
;         __syncthreads();
;         att::attn_body(Q + q0 * NQ + h * 96, KV + t0 * NKV + h * 128, KR + t0 * 32, rope + q0 * 32, O + q0 * DM + h * 64, SEQ, lds_generic, C.tid);
.LA_item:
	s_and_b32 s21, s20, 7
	s_lshr_b32 s10, s20, 3
	s_and_b32 s10, s10, 15
	s_lshr_b32 s11, s20, 7
	s_lshl_b32 s12, s11, 12
	s_lshl_b32 s13, s21, 9
	s_add_u32 s12, s12, s13
	s_lshl_b32 s13, s23, 6
	s_add_u32 s12, s12, s13
	s_mul_i32 s14, s12, 0xc00
	s_mul_i32 s15, s10, 0xc0
	s_add_u32 s14, s14, s15
	s_add_u32 s14, s14, 0xac00000
	s_add_u32 s30, s26, s14
	s_addc_u32 s31, s27, 0
	s_lshl_b32 s14, s12, 7
	s_add_u32 s14, s14, 0x100000
	s_add_u32 s40, s26, s14
	s_addc_u32 s41, s27, 0
	s_lshl_b32 s14, s12, 11
	s_lshl_b32 s15, s10, 7
	s_add_u32 s14, s14, s15
	s_add_u32 s14, s14, 0x6c00000
	s_add_u32 s42, s26, s14
	s_addc_u32 s43, s27, 0
	s_lshl_b32 s14, s11, 24
	s_lshl_b32 s15, s10, 8
	s_add_u32 s14, s14, s15
	s_add_u32 s14, s14, 0x10c00000
	s_add_u32 s28, s26, s14
	s_addc_u32 s29, s27, 0
	s_lshl_b32 s14, s11, 18
	s_add_u32 s14, s14, 0x1d400000
	s_add_u32 s44, s26, s14
	s_addc_u32 s45, s27, 0
	v_add_u32_e32 v247, 0x20000, v243
	global_load_dwordx4 v[228:231], v243, s[28:29]
	global_load_dwordx4 v[130:133], v247, s[28:29]
	global_load_dwordx4 v[248:251], v244, s[44:45]
	s_add_u32 s28, s28, 0x40000
	s_addc_u32 s29, s29, 0
	s_add_u32 s44, s44, 0x1000
	s_addc_u32 s45, s45, 0
	v_and_b32_e32 v245, 31, v211
	v_lshrrev_b32_e32 v246, 5, v211
	v_mul_u32_u24_e32 v247, 0xc00, v245
	v_lshl_add_u32 v247, v246, 4, v247
	v_lshlrev_b32_e32 v202, 7, v245
	v_lshl_add_u32 v202, v246, 5, v202
	global_load_dwordx4 v[142:145], v247, s[30:31] offset:0
	global_load_dwordx4 v[146:149], v247, s[30:31] offset:32
	global_load_dwordx4 v[150:153], v247, s[30:31] offset:64
	global_load_dwordx4 v[154:157], v247, s[30:31] offset:96
	global_load_dwordx4 v[158:161], v247, s[30:31] offset:128
	global_load_dwordx4 v[162:165], v247, s[30:31] offset:160
	global_load_dwordx4 v[66:69], v202, s[40:41] offset:0
	global_load_dwordx4 v[70:73], v202, s[40:41] offset:16
	global_load_dwordx4 v[74:77], v202, s[40:41] offset:64
	global_load_dwordx4 v[78:81], v202, s[40:41] offset:80
	v_add_u32_e32 v247, 0x18000, v247
	v_add_u32_e32 v202, 0x1000, v202
	global_load_dwordx4 v[166:169], v247, s[30:31] offset:0
	global_load_dwordx4 v[170:173], v247, s[30:31] offset:32
	global_load_dwordx4 v[174:177], v247, s[30:31] offset:64
	global_load_dwordx4 v[178:181], v247, s[30:31] offset:96
	global_load_dwordx4 v[182:185], v247, s[30:31] offset:128
	global_load_dwordx4 v[186:189], v247, s[30:31] offset:160
	global_load_dwordx4 v[98:101], v202, s[40:41] offset:0
	global_load_dwordx4 v[102:105], v202, s[40:41] offset:16
	global_load_dwordx4 v[106:109], v202, s[40:41] offset:64
	global_load_dwordx4 v[110:113], v202, s[40:41] offset:80
	v_mov_b32_e32 v141, 0xf149f2ca
	v_mov_b32_e32 v254, 0
	v_mov_b32_e32 v64, 0
	v_mov_b32_e32 v0, 0
	v_mov_b32_e32 v1, 0
	v_mov_b32_e32 v2, 0
	v_mov_b32_e32 v3, 0
	v_mov_b32_e32 v4, 0
	v_mov_b32_e32 v5, 0
	v_mov_b32_e32 v6, 0
	v_mov_b32_e32 v7, 0
	v_mov_b32_e32 v8, 0
	v_mov_b32_e32 v9, 0
	v_mov_b32_e32 v10, 0
	v_mov_b32_e32 v11, 0
	v_mov_b32_e32 v12, 0
	v_mov_b32_e32 v13, 0
	v_mov_b32_e32 v14, 0
	v_mov_b32_e32 v15, 0
	v_mov_b32_e32 v16, 0
	v_mov_b32_e32 v17, 0
	v_mov_b32_e32 v18, 0
	v_mov_b32_e32 v19, 0
	v_mov_b32_e32 v20, 0
	v_mov_b32_e32 v21, 0
	v_mov_b32_e32 v22, 0
	v_mov_b32_e32 v23, 0
	v_mov_b32_e32 v24, 0
	v_mov_b32_e32 v25, 0
	v_mov_b32_e32 v26, 0
	v_mov_b32_e32 v27, 0
	v_mov_b32_e32 v28, 0
	v_mov_b32_e32 v29, 0
	v_mov_b32_e32 v30, 0
	v_mov_b32_e32 v31, 0
	v_mov_b32_e32 v139, 0xf149f2ca
	v_mov_b32_e32 v255, 0
	v_mov_b32_e32 v134, 0
	v_mov_b32_e32 v32, 0
	v_mov_b32_e32 v33, 0
	v_mov_b32_e32 v34, 0
	v_mov_b32_e32 v35, 0
	v_mov_b32_e32 v36, 0
	v_mov_b32_e32 v37, 0
	v_mov_b32_e32 v38, 0
	v_mov_b32_e32 v39, 0
	v_mov_b32_e32 v40, 0
	v_mov_b32_e32 v41, 0
	v_mov_b32_e32 v42, 0
	v_mov_b32_e32 v43, 0
	v_mov_b32_e32 v44, 0
	v_mov_b32_e32 v45, 0
	v_mov_b32_e32 v46, 0
	v_mov_b32_e32 v47, 0
	v_mov_b32_e32 v48, 0
	v_mov_b32_e32 v49, 0
	v_mov_b32_e32 v50, 0
	v_mov_b32_e32 v51, 0
	v_mov_b32_e32 v52, 0
	v_mov_b32_e32 v53, 0
	v_mov_b32_e32 v54, 0
	v_mov_b32_e32 v55, 0
	v_mov_b32_e32 v56, 0
	v_mov_b32_e32 v57, 0
	v_mov_b32_e32 v58, 0
	v_mov_b32_e32 v59, 0
	v_mov_b32_e32 v60, 0
	v_mov_b32_e32 v61, 0
	v_mov_b32_e32 v62, 0
	v_mov_b32_e32 v63, 0
	s_barrier
	s_waitcnt vmcnt(0)
	s_mov_b32 s18, 0
	s_mov_b32 s19, 0x4000
	s_mov_b32 s22, 0x8000
	s_mov_b32 s16, 0
	s_waitcnt vmcnt(0)
	v_add_u32_e32 v246, s18, v240
	v_add_u32_e32 v245, s18, v241
	ds_write_b128 v246, v[228:231]
	ds_write_b128 v245, v[130:133]
	s_cmp_eq_u64 s[2:3], 0
	s_cbranch_scc1 .LA_swp
	v_add_u32_e32 v245, s18, v242
	ds_write_b128 v245, v[248:251] offset:49152
